# v054 g5 converter CUs take 18 more gate/up items per wave (all two-in-flight), barrier sequence 48384 items
# speedup vs baseline: 1.0051x; 1.0051x over previous
; #define WAIT_VM(n) do {} while (0)
; #define LAUNDER_S(x) do {} while (0)
; #define WAIT_VM(n) asm volatile("s_waitcnt vmcnt(" #n ")" ::: "memory")
; #define LAUNDER_S(x) asm volatile("" : "+s"(x))
; DEV int lane_id() { return (int)__builtin_amdgcn_mbcnt_hi(~0u, __builtin_amdgcn_mbcnt_lo(~0u, 0u)); }
; DEV void xcd_barrier(const XcdBarrier& b) {
;     WAIT_VM(0);
;     __syncthreads();
;     int bw = b.wave; LAUNDER_S(bw);
;     if (bw == 0 && lane_id() == 0) {
; DEV void phase_prologue_a(const Frame& F0) {
;     ...
;         constexpr int GU_NB = 2 * FF / 32, GU_ITEMS = 16 * GU_NB;
;         for (int it = F.gw; it < NE * GU_ITEMS; it += F.NGW) { const int e = it / GU_ITEMS, r = it % GU_ITEMS, kb = r / GU_NB, nb = r % GU_NB; const int d0 = 32 * nb, j = d0 >> 8, w = d0 & 255;
.LBB0_115:
	s_or_b64 exec, exec, s[30:31]
	s_cselect_b32 s38, 1, 0
	v_writelane_b32 v255, s38, 61
	v_readlane_b32 s38, v255, 59
	s_add_i32 s39, s38, 1
	v_writelane_b32 v255, s39, 59
	s_mov_b32 s41, 0
	v_readlane_b32 s39, v251, 29
	s_cmp_eq_u32 s39, 0
	s_cbranch_scc1 .Lbw0_none
	v_readlane_b32 s40, v255, 51
	s_cmp_lg_u32 s40, 0x100
	s_cbranch_scc1 .Lbw0_none
	v_readlane_b32 s40, v255, 48
	s_mul_i32 s40, s40, 7
	s_mul_i32 s38, s38, 0x700
	s_add_i32 s40, s40, s38
	s_add_i32 s40, s40, s39
	s_add_i32 s40, s40, -1
	s_cmp_lt_u32 s40, 0xbd00
	s_cbranch_scc0 .Lbw0_none
	s_mov_b32 s41, 0
	s_add_i32 s40, s40, 0x3c00
	s_cmp_lt_u32 s40, 0x7800
	s_cbranch_scc1 .Lbw0_have
	s_mov_b32 s41, 1
	s_sub_i32 s40, s40, 0x7800
	s_cmp_lt_u32 s40, 0x2000
	s_cbranch_scc1 .Lbw0_have
	s_mov_b32 s41, 2
	s_sub_i32 s40, s40, 0x2000
	s_cmp_lt_u32 s40, 0x2000
	s_cbranch_scc1 .Lbw0_have
	s_mov_b32 s41, 3
	s_sub_i32 s40, s40, 0x2000

; #define WAIT_VM(n) do {} while (0)
; #define LAUNDER_S(x) do {} while (0)
; #define WAIT_VM(n) asm volatile("s_waitcnt vmcnt(" #n ")" ::: "memory")
; #define LAUNDER_S(x) asm volatile("" : "+s"(x))
; DEV int lane_id() { return (int)__builtin_amdgcn_mbcnt_hi(~0u, __builtin_amdgcn_mbcnt_lo(~0u, 0u)); }
; DEV void xcd_barrier(const XcdBarrier& b) {
;     WAIT_VM(0);
;     __syncthreads();
;     int bw = b.wave; LAUNDER_S(bw);
;     if (bw == 0 && lane_id() == 0) {
; DEV void phase_prologue_a(const Frame& F0) {
;     ...
;         constexpr int GU_NB = 2 * FF / 32, GU_ITEMS = 16 * GU_NB;
;         for (int it = F.gw; it < NE * GU_ITEMS; it += F.NGW) { const int e = it / GU_ITEMS, r = it % GU_ITEMS, kb = r / GU_NB, nb = r % GU_NB; const int d0 = 32 * nb, j = d0 >> 8, w = d0 & 255;
.LBB0_241:
	v_writelane_b32 v253, s58, 51
	s_nop 1
	v_writelane_b32 v253, s59, 52
	v_writelane_b32 v253, s56, 53
	s_nop 1
	v_writelane_b32 v253, s57, 54
	s_or_b64 exec, exec, s[34:35]
	s_cselect_b32 s38, 1, 0
	v_writelane_b32 v255, s38, 61
	v_readlane_b32 s38, v255, 59
	s_add_i32 s39, s38, 1
	v_writelane_b32 v255, s39, 59
	s_mov_b32 s41, 0
	v_readlane_b32 s39, v251, 29
	s_cmp_eq_u32 s39, 0
	s_cbranch_scc1 .Lbw2_none
	v_readlane_b32 s40, v255, 51
	s_cmp_lg_u32 s40, 0x100
	s_cbranch_scc1 .Lbw2_none
	v_readlane_b32 s40, v255, 48
	s_mul_i32 s40, s40, 7
	s_mul_i32 s38, s38, 0x700
	s_add_i32 s40, s40, s38
	s_add_i32 s40, s40, s39
	s_add_i32 s40, s40, -1
	s_cmp_lt_u32 s40, 0xbd00
	s_cbranch_scc0 .Lbw2_none
	s_mov_b32 s41, 0
	s_add_i32 s40, s40, 0x3c00
	s_cmp_lt_u32 s40, 0x7800
	s_cbranch_scc1 .Lbw2_have
	s_mov_b32 s41, 1
	s_sub_i32 s40, s40, 0x7800
	s_cmp_lt_u32 s40, 0x2000
	s_cbranch_scc1 .Lbw2_have
	s_mov_b32 s41, 2
	s_sub_i32 s40, s40, 0x2000
	s_cmp_lt_u32 s40, 0x2000
	s_cbranch_scc1 .Lbw2_have
	s_mov_b32 s41, 3
	s_sub_i32 s40, s40, 0x2000

; #define WAIT_VM(n) do {} while (0)
; #define LAUNDER_S(x) do {} while (0)
; #define WAIT_VM(n) asm volatile("s_waitcnt vmcnt(" #n ")" ::: "memory")
; #define LAUNDER_S(x) asm volatile("" : "+s"(x))
; DEV int lane_id() { return (int)__builtin_amdgcn_mbcnt_hi(~0u, __builtin_amdgcn_mbcnt_lo(~0u, 0u)); }
; DEV void xcd_barrier(const XcdBarrier& b) {
;     WAIT_VM(0);
;     __syncthreads();
;     int bw = b.wave; LAUNDER_S(bw);
;     if (bw == 0 && lane_id() == 0) {
; DEV void phase_prologue_a(const Frame& F0) {
;     ...
;         constexpr int GU_NB = 2 * FF / 32, GU_ITEMS = 16 * GU_NB;
;         for (int it = F.gw; it < NE * GU_ITEMS; it += F.NGW) { const int e = it / GU_ITEMS, r = it % GU_ITEMS, kb = r / GU_NB, nb = r % GU_NB; const int d0 = 32 * nb, j = d0 >> 8, w = d0 & 255;
.LBB0_422:
	s_or_b64 exec, exec, s[34:35]
	s_cselect_b32 s38, 1, 0
	v_writelane_b32 v255, s38, 61
	v_readlane_b32 s38, v255, 59
	s_add_i32 s39, s38, 1
	v_writelane_b32 v255, s39, 59
	s_mov_b32 s41, 0
	v_readlane_b32 s39, v251, 29
	s_cmp_eq_u32 s39, 0
	s_cbranch_scc1 .Lbw3_none
	v_readlane_b32 s40, v255, 51
	s_cmp_lg_u32 s40, 0x100
	s_cbranch_scc1 .Lbw3_none
	v_readlane_b32 s40, v255, 48
	s_mul_i32 s40, s40, 7
	s_mul_i32 s38, s38, 0x700
	s_add_i32 s40, s40, s38
	s_add_i32 s40, s40, s39
	s_add_i32 s40, s40, -1
	s_cmp_lt_u32 s40, 0xbd00
	s_cbranch_scc0 .Lbw3_none
	s_mov_b32 s41, 0
	s_add_i32 s40, s40, 0x3c00
	s_cmp_lt_u32 s40, 0x7800
	s_cbranch_scc1 .Lbw3_have
	s_mov_b32 s41, 1
	s_sub_i32 s40, s40, 0x7800
	s_cmp_lt_u32 s40, 0x2000
	s_cbranch_scc1 .Lbw3_have
	s_mov_b32 s41, 2
	s_sub_i32 s40, s40, 0x2000
	s_cmp_lt_u32 s40, 0x2000
	s_cbranch_scc1 .Lbw3_have
	s_mov_b32 s41, 3
	s_sub_i32 s40, s40, 0x2000

; #define WAIT_VM(n) do {} while (0)
; #define LAUNDER_S(x) do {} while (0)
; #define WAIT_VM(n) asm volatile("s_waitcnt vmcnt(" #n ")" ::: "memory")
; #define LAUNDER_S(x) asm volatile("" : "+s"(x))
; DEV int lane_id() { return (int)__builtin_amdgcn_mbcnt_hi(~0u, __builtin_amdgcn_mbcnt_lo(~0u, 0u)); }
; DEV void xcd_barrier(const XcdBarrier& b) {
;     WAIT_VM(0);
;     __syncthreads();
;     int bw = b.wave; LAUNDER_S(bw);
;     if (bw == 0 && lane_id() == 0) {
; DEV void phase_prologue_a(const Frame& F0) {
;     ...
;         constexpr int GU_NB = 2 * FF / 32, GU_ITEMS = 16 * GU_NB;
;         for (int it = F.gw; it < NE * GU_ITEMS; it += F.NGW) { const int e = it / GU_ITEMS, r = it % GU_ITEMS, kb = r / GU_NB, nb = r % GU_NB; const int d0 = 32 * nb, j = d0 >> 8, w = d0 & 255;
.Lxb4_join:
.LBB0_811:
	s_or_b64 exec, exec, s[34:35]
	s_cselect_b32 s38, 1, 0
	v_writelane_b32 v255, s38, 61
	v_readlane_b32 s38, v255, 59
	s_add_i32 s39, s38, 1
	v_writelane_b32 v255, s39, 59
	s_mov_b32 s41, 0
	v_readlane_b32 s39, v251, 29
	s_cmp_eq_u32 s39, 0
	s_cbranch_scc1 .Lbw4_none
	v_readlane_b32 s40, v255, 51
	s_cmp_lg_u32 s40, 0x100
	s_cbranch_scc1 .Lbw4_none
	v_readlane_b32 s40, v255, 48
	s_mul_i32 s40, s40, 7
	s_mul_i32 s38, s38, 0x700
	s_add_i32 s40, s40, s38
	s_add_i32 s40, s40, s39
	s_add_i32 s40, s40, -1
	s_cmp_lt_u32 s40, 0xbd00
	s_cbranch_scc0 .Lbw4_none
	s_mov_b32 s41, 0
	s_add_i32 s40, s40, 0x3c00
	s_cmp_lt_u32 s40, 0x7800
	s_cbranch_scc1 .Lbw4_have
	s_mov_b32 s41, 1
	s_sub_i32 s40, s40, 0x7800
	s_cmp_lt_u32 s40, 0x2000
	s_cbranch_scc1 .Lbw4_have
	s_mov_b32 s41, 2
	s_sub_i32 s40, s40, 0x2000
	s_cmp_lt_u32 s40, 0x2000
	s_cbranch_scc1 .Lbw4_have
	s_mov_b32 s41, 3
	s_sub_i32 s40, s40, 0x2000

; #define WAVE_LDS_SYNC() do { int _z = 0; (void)emu::wave_xchg(&_z, 4); } while (0)
; #define LAS __attribute__((address_space(3)))
; #define WAVE_LDS_SYNC() asm volatile("s_waitcnt lgkmcnt(0)" ::: "memory")
; #define NT_LOAD(p) __builtin_nontemporal_load(p)
; DEV void tr_item(const float* W, int ldw, int col0, int k0, bf16_t* WT, int K, int row0, LAS float* scr, int lane) {
;     ...
;     for (int i = 0; i < 32; ++i) { const int kk = 2 * i + (lane >> 5); scr[kk * 33 + (lane & 31)] = NT_LOAD(&W[(size_t)(k0 + kk) * ldw + col0 + (lane & 31)]); }
;     WAVE_LDS_SYNC();
;     const int c = lane & 7;
; #pragma unroll
;     for (int j = 0; j < 4; ++j) { const int n = (lane >> 3) + 8 * j; const LAS float* s = scr + (8 * c) * 33 + n;
; DEV void phase_prologue_a(const Frame& F0) {
;     ...
;         constexpr int GU_NB = 2 * FF / 32, GU_ITEMS = 16 * GU_NB;
;         for (int it = F.gw; it < NE * GU_ITEMS; it += F.NGW) { const int e = it / GU_ITEMS, r = it % GU_ITEMS, kb = r / GU_NB, nb = r % GU_NB; const int d0 = 32 * nb, j = d0 >> 8, w = d0 & 255;
;             const float* src = (w < 128 ? GIN(I_WGATE) : GIN(I_WUP)) + ((size_t)l * NE + e) * 1024 * FF;
;             tr_item(src, FF, 128 * j + (w & 127), 64 * kb, (bf16_t*)(F.ws + WS_WGU) + ((size_t)l * NE + e) * 2 * FF * 1024, 1024, d0, scr, F.lane); }
.Lsg_entry:
	v_readlane_b32 s36, v253, 62
	s_cmp_gt_u32 s36, 2
	s_cbranch_scc1 .Lsg_done
	v_readlane_b32 s2, v255, 51
	s_cmp_lg_u32 s2, 0x100
	s_cbranch_scc1 .Lsg_done
	v_readlane_b32 s2, v255, 48
	s_cmp_lt_u32 s2, 0x88
	s_cbranch_scc1 .Lsg_done
	v_readlane_b32 s3, v251, 29
	s_sub_i32 s2, s2, 0x88
	s_lshl_b32 s2, s2, 3
	s_add_i32 s2, s2, s3
	v_readlane_b32 s6, v255, 53
	v_readlane_b32 s7, v255, 54
	v_readlane_b32 s4, v255, 55
	v_readlane_b32 s5, v255, 56
	v_readlane_b32 s34, v255, 57
	v_readlane_b32 s35, v255, 58
	s_add_u32 s6, s6, 0x2bc8000
	s_addc_u32 s7, s7, 0
	s_mov_b32 s8, 0
	s_mov_b32 s37, 0
	s_cmp_eq_u32 s36, 0
	s_cbranch_scc1 .Lsg_go
	s_mov_b32 s8, 0x8000000
	s_mov_b32 s37, 0x4400
	s_cmp_eq_u32 s36, 1
	s_cbranch_scc1 .Lsg_go
	s_mov_b32 s8, 0x10000000
	s_mov_b32 s37, 0x4400

; #define LAS __attribute__((address_space(3)))
; #define NT_LOAD(p) __builtin_nontemporal_load(p)
; DEV void tr_item(const float* W, int ldw, int col0, int k0, bf16_t* WT, int K, int row0, LAS float* scr, int lane) {
; #pragma unroll 8
;     for (int i = 0; i < 32; ++i) { const int kk = 2 * i + (lane >> 5); scr[kk * 33 + (lane & 31)] = NT_LOAD(&W[(size_t)(k0 + kk) * ldw + col0 + (lane & 31)]); }
; DEV void phase_prologue_a(const Frame& F0) {
;     ...
;         constexpr int D_ITEMS = (FF / 64) * 32;
;         for (int it = F.gw; it < NE * D_ITEMS; it += F.NGW) { const int e = it / D_ITEMS, r = it % D_ITEMS, kb = r / 32, nb = r % 32;
;             tr_item(GIN(I_WDOWN) + ((size_t)l * NE + e) * FF * 1024, 1024, 32 * nb, 64 * kb, (bf16_t*)(F.ws + WS_WD) + ((size_t)l * NE + e) * 1024 * FF, FF, 32 * nb, scr, F.lane); }
.Lsd_loop:
	s_lshr_b32 s8, s2, 10
	s_and_b32 s9, s2, 0x3ff
	s_lshr_b32 s10, s9, 5
	s_and_b32 s9, s9, 31
	s_lshl_b32 s24, s10, 18
	s_lshl_b32 s25, s9, 7
	s_add_i32 s24, s24, s25
	s_lshr_b32 s29, s8, 9
	s_lshl_b32 s28, s8, 23
	s_add_u32 s28, s28, s24
	s_addc_u32 s29, s29, 0
	s_add_u32 s28, s28, s4
	s_addc_u32 s29, s29, s5
	s_lshl_b32 s24, s9, 17
	s_lshl_b32 s25, s10, 7
	s_add_i32 s24, s24, s25
	s_lshr_b32 s11, s8, 10
	s_lshl_b32 s10, s8, 22
	s_add_u32 s10, s10, s24
	s_addc_u32 s11, s11, 0
	s_add_u32 s10, s10, s6
	s_addc_u32 s11, s11, s7
	v_lshl_add_u64 v[16:17], s[28:29], 0, v[122:123]
	v_lshl_add_u64 v[18:19], v[16:17], 0, s[44:45]
	v_lshl_add_u64 v[20:21], v[18:19], 0, s[44:45]
	v_lshl_add_u64 v[22:23], v[20:21], 0, s[44:45]
	v_lshl_add_u64 v[24:25], v[22:23], 0, s[44:45]
	v_lshl_add_u64 v[26:27], v[24:25], 0, s[44:45]
	v_lshl_add_u64 v[28:29], v[26:27], 0, s[44:45]
	v_lshl_add_u64 v[30:31], v[28:29], 0, s[44:45]
	global_load_dword v32, v[16:17], off nt
	global_load_dword v33, v[18:19], off nt
	global_load_dword v34, v[20:21], off nt
	global_load_dword v35, v[22:23], off nt
	global_load_dword v36, v[24:25], off nt
	global_load_dword v37, v[26:27], off nt
	global_load_dword v38, v[28:29], off nt
	global_load_dword v39, v[30:31], off nt
	v_lshl_add_u64 v[16:17], v[16:17], 0, s[40:41]
	v_lshl_add_u64 v[18:19], v[18:19], 0, s[40:41]
	v_lshl_add_u64 v[20:21], v[20:21], 0, s[40:41]
	v_lshl_add_u64 v[22:23], v[22:23], 0, s[40:41]
	v_lshl_add_u64 v[24:25], v[24:25], 0, s[40:41]
	v_lshl_add_u64 v[26:27], v[26:27], 0, s[40:41]
	v_lshl_add_u64 v[28:29], v[28:29], 0, s[40:41]
	v_lshl_add_u64 v[30:31], v[30:31], 0, s[40:41]
	global_load_dword v40, v[16:17], off nt
	global_load_dword v41, v[18:19], off nt
	global_load_dword v42, v[20:21], off nt
	global_load_dword v43, v[22:23], off nt
	global_load_dword v44, v[24:25], off nt
	global_load_dword v45, v[26:27], off nt
	global_load_dword v46, v[28:29], off nt
	global_load_dword v47, v[30:31], off nt
	v_lshl_add_u64 v[16:17], v[16:17], 0, s[40:41]
	v_lshl_add_u64 v[18:19], v[18:19], 0, s[40:41]
	v_lshl_add_u64 v[20:21], v[20:21], 0, s[40:41]
	v_lshl_add_u64 v[22:23], v[22:23], 0, s[40:41]
	v_lshl_add_u64 v[24:25], v[24:25], 0, s[40:41]
	v_lshl_add_u64 v[26:27], v[26:27], 0, s[40:41]
	v_lshl_add_u64 v[28:29], v[28:29], 0, s[40:41]
	v_lshl_add_u64 v[30:31], v[30:31], 0, s[40:41]
	global_load_dword v48, v[16:17], off nt
	global_load_dword v49, v[18:19], off nt
	global_load_dword v50, v[20:21], off nt
	global_load_dword v51, v[22:23], off nt
	global_load_dword v52, v[24:25], off nt
	global_load_dword v53, v[26:27], off nt
	global_load_dword v54, v[28:29], off nt
	global_load_dword v55, v[30:31], off nt
	v_lshl_add_u64 v[16:17], v[16:17], 0, s[40:41]
	v_lshl_add_u64 v[18:19], v[18:19], 0, s[40:41]
	v_lshl_add_u64 v[20:21], v[20:21], 0, s[40:41]
	v_lshl_add_u64 v[22:23], v[22:23], 0, s[40:41]
	v_lshl_add_u64 v[24:25], v[24:25], 0, s[40:41]
	v_lshl_add_u64 v[26:27], v[26:27], 0, s[40:41]
	v_lshl_add_u64 v[28:29], v[28:29], 0, s[40:41]
	v_lshl_add_u64 v[30:31], v[30:31], 0, s[40:41]
	global_load_dword v56, v[16:17], off nt
	global_load_dword v57, v[18:19], off nt
	global_load_dword v58, v[20:21], off nt
	global_load_dword v59, v[22:23], off nt
	global_load_dword v60, v[24:25], off nt
	global_load_dword v61, v[26:27], off nt
	global_load_dword v62, v[28:29], off nt
	global_load_dword v63, v[30:31], off nt
	v_lshl_add_u64 v[64:65], s[10:11], 0, v[124:125]
	v_lshl_add_u64 v[66:67], v[64:65], 0, s[42:43]
	v_lshl_add_u64 v[68:69], v[66:67], 0, s[42:43]
	v_lshl_add_u64 v[70:71], v[68:69], 0, s[42:43]
	s_add_i32 s31, s2, 0x200
	s_lshr_b32 s8, s31, 10
	s_and_b32 s9, s31, 0x3ff
	s_lshr_b32 s10, s9, 5
	s_and_b32 s9, s9, 31
	s_lshl_b32 s24, s10, 18
	s_lshl_b32 s25, s9, 7
	s_add_i32 s24, s24, s25
	s_lshr_b32 s29, s8, 9
	s_lshl_b32 s28, s8, 23
	s_add_u32 s28, s28, s24
	s_addc_u32 s29, s29, 0
	s_add_u32 s28, s28, s4
	s_addc_u32 s29, s29, s5
	s_lshl_b32 s24, s9, 17
	s_lshl_b32 s25, s10, 7
	s_add_i32 s24, s24, s25
	s_lshr_b32 s11, s8, 10
	s_lshl_b32 s10, s8, 22
	s_add_u32 s10, s10, s24
	s_addc_u32 s11, s11, 0
	s_add_u32 s10, s10, s6
	s_addc_u32 s11, s11, s7
	v_lshl_add_u64 v[16:17], s[28:29], 0, v[122:123]
	v_lshl_add_u64 v[18:19], v[16:17], 0, s[44:45]
	v_lshl_add_u64 v[20:21], v[18:19], 0, s[44:45]
	v_lshl_add_u64 v[22:23], v[20:21], 0, s[44:45]
	v_lshl_add_u64 v[24:25], v[22:23], 0, s[44:45]
	v_lshl_add_u64 v[26:27], v[24:25], 0, s[44:45]
	v_lshl_add_u64 v[28:29], v[26:27], 0, s[44:45]
	v_lshl_add_u64 v[30:31], v[28:29], 0, s[44:45]
	global_load_dword v126, v[16:17], off nt
	global_load_dword v127, v[18:19], off nt
	global_load_dword v128, v[20:21], off nt
	global_load_dword v129, v[22:23], off nt
	global_load_dword v130, v[24:25], off nt
	global_load_dword v131, v[26:27], off nt
	global_load_dword v132, v[28:29], off nt
	global_load_dword v133, v[30:31], off nt
	v_lshl_add_u64 v[16:17], v[16:17], 0, s[40:41]
	v_lshl_add_u64 v[18:19], v[18:19], 0, s[40:41]
	v_lshl_add_u64 v[20:21], v[20:21], 0, s[40:41]
	v_lshl_add_u64 v[22:23], v[22:23], 0, s[40:41]
	v_lshl_add_u64 v[24:25], v[24:25], 0, s[40:41]
	v_lshl_add_u64 v[26:27], v[26:27], 0, s[40:41]
	v_lshl_add_u64 v[28:29], v[28:29], 0, s[40:41]
	v_lshl_add_u64 v[30:31], v[30:31], 0, s[40:41]
	global_load_dword v134, v[16:17], off nt
	global_load_dword v135, v[18:19], off nt
	global_load_dword v136, v[20:21], off nt
	global_load_dword v137, v[22:23], off nt
	global_load_dword v138, v[24:25], off nt
	global_load_dword v139, v[26:27], off nt
	global_load_dword v140, v[28:29], off nt
	global_load_dword v141, v[30:31], off nt
	v_lshl_add_u64 v[16:17], v[16:17], 0, s[40:41]
; #define WAVE_LDS_SYNC() do { int _z = 0; (void)emu::wave_xchg(&_z, 4); } while (0)
; #define LAS __attribute__((address_space(3)))
; #define WAVE_LDS_SYNC() asm volatile("s_waitcnt lgkmcnt(0)" ::: "memory")
; #define NT_LOAD(p) __builtin_nontemporal_load(p)
; DEV void tr_item(const float* W, int ldw, int col0, int k0, bf16_t* WT, int K, int row0, LAS float* scr, int lane) {
; #pragma unroll 8
;     for (int i = 0; i < 32; ++i) { const int kk = 2 * i + (lane >> 5); scr[kk * 33 + (lane & 31)] = NT_LOAD(&W[(size_t)(k0 + kk) * ldw + col0 + (lane & 31)]); }
;     WAVE_LDS_SYNC();
;     const int c = lane & 7;
; #pragma unroll
;     for (int j = 0; j < 4; ++j) { const int n = (lane >> 3) + 8 * j; const LAS float* s = scr + (8 * c) * 33 + n;
	v_lshl_add_u64 v[18:19], v[18:19], 0, s[40:41]
	v_lshl_add_u64 v[20:21], v[20:21], 0, s[40:41]
	v_lshl_add_u64 v[22:23], v[22:23], 0, s[40:41]
	v_lshl_add_u64 v[24:25], v[24:25], 0, s[40:41]
	v_lshl_add_u64 v[26:27], v[26:27], 0, s[40:41]
	v_lshl_add_u64 v[28:29], v[28:29], 0, s[40:41]
	v_lshl_add_u64 v[30:31], v[30:31], 0, s[40:41]
	global_load_dword v142, v[16:17], off nt
	global_load_dword v143, v[18:19], off nt
	global_load_dword v144, v[20:21], off nt
	global_load_dword v145, v[22:23], off nt
	global_load_dword v150, v[24:25], off nt
	global_load_dword v151, v[26:27], off nt
	global_load_dword v152, v[28:29], off nt
	global_load_dword v153, v[30:31], off nt
	v_lshl_add_u64 v[16:17], v[16:17], 0, s[40:41]
	v_lshl_add_u64 v[18:19], v[18:19], 0, s[40:41]
	v_lshl_add_u64 v[20:21], v[20:21], 0, s[40:41]
	v_lshl_add_u64 v[22:23], v[22:23], 0, s[40:41]
	v_lshl_add_u64 v[24:25], v[24:25], 0, s[40:41]
	v_lshl_add_u64 v[26:27], v[26:27], 0, s[40:41]
	v_lshl_add_u64 v[28:29], v[28:29], 0, s[40:41]
	v_lshl_add_u64 v[30:31], v[30:31], 0, s[40:41]
	global_load_dword v154, v[16:17], off nt
	global_load_dword v155, v[18:19], off nt
	global_load_dword v156, v[20:21], off nt
	global_load_dword v157, v[22:23], off nt
	global_load_dword v158, v[24:25], off nt
	global_load_dword v159, v[26:27], off nt
	global_load_dword v160, v[28:29], off nt
	global_load_dword v161, v[30:31], off nt
	v_lshl_add_u64 v[162:163], s[10:11], 0, v[124:125]
	v_lshl_add_u64 v[164:165], v[162:163], 0, s[42:43]
	v_lshl_add_u64 v[166:167], v[164:165], 0, s[42:43]
	v_lshl_add_u64 v[168:169], v[166:167], 0, s[42:43]
	s_waitcnt vmcnt(62)
	ds_write2_b32 v7, v32, v33 offset1:66
	s_waitcnt vmcnt(60)
	ds_write2_b32 v7, v34, v35 offset0:132 offset1:198
	s_waitcnt vmcnt(58)
	ds_write2_b32 v8, v36, v37 offset0:8 offset1:74
	s_waitcnt vmcnt(56)
	ds_write2_b32 v8, v38, v39 offset0:140 offset1:206
	s_waitcnt vmcnt(54)
	ds_write2_b32 v9, v40, v41 offset1:66
	s_waitcnt vmcnt(52)
	ds_write2_b32 v9, v42, v43 offset0:132 offset1:198
	s_waitcnt vmcnt(50)
	ds_write2_b32 v10, v44, v45 offset0:8 offset1:74
	s_waitcnt vmcnt(48)
	ds_write2_b32 v10, v46, v47 offset0:140 offset1:206
	s_waitcnt vmcnt(46)
	ds_write2_b32 v11, v48, v49 offset1:66
	s_waitcnt vmcnt(44)
	ds_write2_b32 v11, v50, v51 offset0:132 offset1:198
	s_waitcnt vmcnt(42)
	ds_write2_b32 v12, v52, v53 offset0:8 offset1:74
	s_waitcnt vmcnt(40)
	ds_write2_b32 v12, v54, v55 offset0:140 offset1:206
	s_waitcnt vmcnt(38)
	ds_write2_b32 v13, v56, v57 offset1:66
	s_waitcnt vmcnt(36)
	ds_write2_b32 v13, v58, v59 offset0:132 offset1:198
	s_waitcnt vmcnt(34)
	ds_write2_b32 v14, v60, v61 offset0:8 offset1:74
	s_waitcnt vmcnt(32)
	ds_write2_b32 v14, v62, v63 offset0:140 offset1:206
	ds_read2_b32 v[72:73], v15 offset1:8
	ds_read2_b32 v[74:75], v15 offset0:33 offset1:41
	ds_read2_b32 v[76:77], v15 offset0:66 offset1:74
	ds_read2_b32 v[78:79], v15 offset0:99 offset1:107
	ds_read2_b32 v[80:81], v15 offset0:132 offset1:140
	ds_read2_b32 v[82:83], v15 offset0:165 offset1:173
	ds_read2_b32 v[84:85], v15 offset0:198 offset1:206
	ds_read2_b32 v[86:87], v15 offset0:231 offset1:239
	ds_read2_b32 v[88:89], v15 offset0:16 offset1:24
	ds_read2_b32 v[90:91], v15 offset0:49 offset1:57
	ds_read2_b32 v[92:93], v15 offset0:82 offset1:90
	ds_read2_b32 v[94:95], v15 offset0:115 offset1:123
	s_waitcnt lgkmcnt(4)
	v_cvt_pk_bf16_f32 v104, v72, v74
	v_cvt_pk_bf16_f32 v105, v76, v78
	v_cvt_pk_bf16_f32 v106, v80, v82
	v_cvt_pk_bf16_f32 v107, v84, v86
	v_cvt_pk_bf16_f32 v108, v73, v75
	v_cvt_pk_bf16_f32 v109, v77, v79
	v_cvt_pk_bf16_f32 v110, v81, v83
	v_cvt_pk_bf16_f32 v111, v85, v87
	ds_read2_b32 v[96:97], v15 offset0:148 offset1:156
	ds_read2_b32 v[98:99], v15 offset0:181 offset1:189
	ds_read2_b32 v[100:101], v15 offset0:214 offset1:222
	ds_read2_b32 v[102:103], v15 offset0:247 offset1:255
	global_store_dwordx4 v[64:65], v[104:107], off nt
	global_store_dwordx4 v[66:67], v[108:111], off nt
	s_waitcnt lgkmcnt(0)
	v_cvt_pk_bf16_f32 v112, v88, v90
	v_cvt_pk_bf16_f32 v113, v92, v94
	v_cvt_pk_bf16_f32 v114, v96, v98
	v_cvt_pk_bf16_f32 v115, v100, v102
	v_cvt_pk_bf16_f32 v116, v89, v91
	v_cvt_pk_bf16_f32 v117, v93, v95
	v_cvt_pk_bf16_f32 v118, v97, v99
	v_cvt_pk_bf16_f32 v119, v101, v103
	global_store_dwordx4 v[68:69], v[112:115], off nt
	global_store_dwordx4 v[70:71], v[116:119], off nt
	s_waitcnt vmcnt(34)
	ds_write2_b32 v7, v126, v127 offset1:66
	s_waitcnt vmcnt(32)
	ds_write2_b32 v7, v128, v129 offset0:132 offset1:198
	s_waitcnt vmcnt(30)
	ds_write2_b32 v8, v130, v131 offset0:8 offset1:74
	s_waitcnt vmcnt(28)
	ds_write2_b32 v8, v132, v133 offset0:140 offset1:206
	s_waitcnt vmcnt(26)
	ds_write2_b32 v9, v134, v135 offset1:66
	s_waitcnt vmcnt(24)
	ds_write2_b32 v9, v136, v137 offset0:132 offset1:198
	s_waitcnt vmcnt(22)
	ds_write2_b32 v10, v138, v139 offset0:8 offset1:74
	s_waitcnt vmcnt(20)
	ds_write2_b32 v10, v140, v141 offset0:140 offset1:206
	s_waitcnt vmcnt(18)
	ds_write2_b32 v11, v142, v143 offset1:66
	s_waitcnt vmcnt(16)
	ds_write2_b32 v11, v144, v145 offset0:132 offset1:198
	s_waitcnt vmcnt(14)
	ds_write2_b32 v12, v150, v151 offset0:8 offset1:74
	s_waitcnt vmcnt(12)
	ds_write2_b32 v12, v152, v153 offset0:140 offset1:206
	s_waitcnt vmcnt(10)
	ds_write2_b32 v13, v154, v155 offset1:66
	s_waitcnt vmcnt(8)
	ds_write2_b32 v13, v156, v157 offset0:132 offset1:198
	s_waitcnt vmcnt(6)
	ds_write2_b32 v14, v158, v159 offset0:8 offset1:74
	s_waitcnt vmcnt(4)
; #define WAVE_LDS_SYNC() do { int _z = 0; (void)emu::wave_xchg(&_z, 4); } while (0)
; #define LAS __attribute__((address_space(3)))
; #define WAVE_LDS_SYNC() asm volatile("s_waitcnt lgkmcnt(0)" ::: "memory")
; #define NT_LOAD(p) __builtin_nontemporal_load(p)
; #define NT_STORE(v, p) __builtin_nontemporal_store((v), (p))
; DEV unsigned pk2(float lo, float hi) { return f2bf(lo) | (f2bf(hi) << 16); }
; DEV unsigned pk2(float lo, float hi) { const f32x2n_t v = {lo, hi}; return __builtin_bit_cast(unsigned, __builtin_convertvector(v, bf16x2n_t)); }
; DEV void tr_item(const float* W, int ldw, int col0, int k0, bf16_t* WT, int K, int row0, LAS float* scr, int lane) {
;     ...
;     for (int i = 0; i < 32; ++i) { const int kk = 2 * i + (lane >> 5); scr[kk * 33 + (lane & 31)] = NT_LOAD(&W[(size_t)(k0 + kk) * ldw + col0 + (lane & 31)]); }
;     WAVE_LDS_SYNC();
;     const int c = lane & 7;
; #pragma unroll
;     for (int j = 0; j < 4; ++j) { const int n = (lane >> 3) + 8 * j; const LAS float* s = scr + (8 * c) * 33 + n;
;         u32x4 o; o.x = pk2(s[0 * 33], s[1 * 33]); o.y = pk2(s[2 * 33], s[3 * 33]); o.z = pk2(s[4 * 33], s[5 * 33]); o.w = pk2(s[6 * 33], s[7 * 33]);
;         NT_STORE(o, (u32x4*)(WT + (size_t)(row0 + n) * K + k0 + 8 * c)); }
;     WAVE_LDS_SYNC();
; DEV void phase_prologue_a(const Frame& F0) {
;     ...
;         constexpr int GU_NB = 2 * FF / 32, GU_ITEMS = 16 * GU_NB;
;         for (int it = F.gw; it < NE * GU_ITEMS; it += F.NGW) { const int e = it / GU_ITEMS, r = it % GU_ITEMS, kb = r / GU_NB, nb = r % GU_NB; const int d0 = 32 * nb, j = d0 >> 8, w = d0 & 255;
;             const float* src = (w < 128 ? GIN(I_WGATE) : GIN(I_WUP)) + ((size_t)l * NE + e) * 1024 * FF;
;             tr_item(src, FF, 128 * j + (w & 127), 64 * kb, (bf16_t*)(F.ws + WS_WGU) + ((size_t)l * NE + e) * 2 * FF * 1024, 1024, d0, scr, F.lane); }
	ds_write2_b32 v14, v160, v161 offset0:140 offset1:206
	ds_read2_b32 v[72:73], v15 offset1:8
	ds_read2_b32 v[74:75], v15 offset0:33 offset1:41
	ds_read2_b32 v[76:77], v15 offset0:66 offset1:74
	ds_read2_b32 v[78:79], v15 offset0:99 offset1:107
	ds_read2_b32 v[80:81], v15 offset0:132 offset1:140
	ds_read2_b32 v[82:83], v15 offset0:165 offset1:173
	ds_read2_b32 v[84:85], v15 offset0:198 offset1:206
	ds_read2_b32 v[86:87], v15 offset0:231 offset1:239
	ds_read2_b32 v[88:89], v15 offset0:16 offset1:24
	ds_read2_b32 v[90:91], v15 offset0:49 offset1:57
	ds_read2_b32 v[92:93], v15 offset0:82 offset1:90
	ds_read2_b32 v[94:95], v15 offset0:115 offset1:123
	s_waitcnt lgkmcnt(4)
	v_cvt_pk_bf16_f32 v104, v72, v74
	v_cvt_pk_bf16_f32 v105, v76, v78
	v_cvt_pk_bf16_f32 v106, v80, v82
	v_cvt_pk_bf16_f32 v107, v84, v86
	v_cvt_pk_bf16_f32 v108, v73, v75
	v_cvt_pk_bf16_f32 v109, v77, v79
	v_cvt_pk_bf16_f32 v110, v81, v83
	v_cvt_pk_bf16_f32 v111, v85, v87
	ds_read2_b32 v[96:97], v15 offset0:148 offset1:156
	ds_read2_b32 v[98:99], v15 offset0:181 offset1:189
	ds_read2_b32 v[100:101], v15 offset0:214 offset1:222
	ds_read2_b32 v[102:103], v15 offset0:247 offset1:255
	global_store_dwordx4 v[162:163], v[104:107], off nt
	global_store_dwordx4 v[164:165], v[108:111], off nt
	s_waitcnt lgkmcnt(0)
	v_cvt_pk_bf16_f32 v112, v88, v90
	v_cvt_pk_bf16_f32 v113, v92, v94
	v_cvt_pk_bf16_f32 v114, v96, v98
	v_cvt_pk_bf16_f32 v115, v100, v102
	v_cvt_pk_bf16_f32 v116, v89, v91
	v_cvt_pk_bf16_f32 v117, v93, v95
	v_cvt_pk_bf16_f32 v118, v97, v99
	v_cvt_pk_bf16_f32 v119, v101, v103
	global_store_dwordx4 v[166:167], v[112:115], off nt
	global_store_dwordx4 v[168:169], v[116:119], off nt
	s_addk_i32 s2, 0x400
	s_cmp_lt_u32 s2, 0x4000
	s_cbranch_scc1 .Lsd_loop
	s_mov_b32 s36, 1
	s_mov_b32 s37, 0x2000
	s_cmp_eq_u32 s0, 1
	s_cbranch_scc1 .Lsx_go
	s_mov_b32 s36, 2
	s_cmp_eq_u32 s0, 2
	s_cbranch_scc1 .Lsx_go
	s_mov_b32 s36, 3
	s_mov_b32 s37, 0x4100
.Lsx_go:
	v_readlane_b32 s2, v255, 48
	v_readlane_b32 s3, v251, 29
	s_sub_i32 s2, s2, 0xc0
	s_lshl_b32 s2, s2, 3
	s_add_i32 s2, s2, s3
	s_add_i32 s2, s2, s37
	s_add_i32 s101, s37, 0x2400
	v_readlane_b32 s6, v255, 53
	v_readlane_b32 s7, v255, 54
	v_readlane_b32 s4, v255, 55
	v_readlane_b32 s5, v255, 56
	v_readlane_b32 s34, v255, 57
	v_readlane_b32 s35, v255, 58
	s_add_u32 s6, s6, 0x2bc8000
	s_addc_u32 s7, s7, 0
	s_lshl_b32 s8, s36, 27
	s_add_u32 s4, s4, s8
	s_addc_u32 s5, s5, 0
	s_add_u32 s34, s34, s8
	s_addc_u32 s35, s35, 0
	s_add_u32 s6, s6, s8
	s_addc_u32 s7, s7, 0
	s_waitcnt vmcnt(0) lgkmcnt(0)
	s_lshl_b32 s30, s3, 14
	v_and_b32_e32 v120, 31, v200
	v_lshlrev_b32_e32 v2, 2, v120
	v_lshrrev_b32_e32 v3, 5, v200
	v_and_b32_e32 v4, 7, v200
	v_lshrrev_b32_e32 v6, 3, v200
	v_mul_u32_u24_e32 v7, 33, v3
	v_add_u32_e32 v7, v7, v120
	v_lshl_add_u32 v7, v7, 2, s30
	v_add_u32_e32 v8, 0x400, v7
	v_add_u32_e32 v9, 0x840, v7
	v_add_u32_e32 v10, 0xc40, v7
	v_add_u32_e32 v11, 0x1080, v7
	v_add_u32_e32 v12, 0x1480, v7
	v_add_u32_e32 v13, 0x18c0, v7
	v_add_u32_e32 v14, 0x1cc0, v7
	v_mul_u32_u24_e32 v120, 0x108, v4
	v_add_u32_e32 v120, v120, v6
	v_lshl_add_u32 v15, v120, 2, s30
	v_lshl_add_u32 v122, v3, 13, v2
	v_mov_b32_e32 v123, 0
	v_lshlrev_b32_e32 v124, 4, v4
	v_lshl_add_u32 v124, v6, 11, v124
	v_mov_b32_e32 v125, 0
	s_mov_b64 s[40:41], 0x20000
	s_mov_b64 s[42:43], 0x4000
	s_mov_b64 s[44:45], 0x4000
.Lsx_loop:
	s_lshr_b32 s8, s2, 11
	s_and_b32 s9, s2, 0x7ff
	s_lshr_b32 s10, s9, 7
	s_and_b32 s9, s9, 0x7f
	s_lshl_b32 s24, s10, 19
	s_lshr_b32 s25, s9, 3
	s_lshl_b32 s25, s25, 9
	s_add_i32 s24, s24, s25
	s_and_b32 s25, s9, 3
	s_lshl_b32 s25, s25, 7
	s_add_i32 s24, s24, s25
	s_lshr_b32 s29, s8, 9
	s_lshl_b32 s28, s8, 23
	s_add_u32 s28, s28, s24
	s_addc_u32 s29, s29, 0
	s_bitcmp0_b32 s9, 2
	s_cselect_b32 s24, s4, s34
	s_cselect_b32 s25, s5, s35
	s_add_u32 s28, s28, s24
	s_addc_u32 s29, s29, s25
	s_lshl_b32 s24, s9, 16
	s_lshl_b32 s25, s10, 7
	s_add_i32 s24, s24, s25
	s_lshr_b32 s11, s8, 9
	s_lshl_b32 s10, s8, 23
	s_add_u32 s10, s10, s24
	s_addc_u32 s11, s11, 0
	s_add_u32 s10, s10, s6
	s_addc_u32 s11, s11, s7
	v_lshl_add_u64 v[16:17], s[28:29], 0, v[122:123]
	v_lshl_add_u64 v[18:19], v[16:17], 0, s[44:45]
	v_lshl_add_u64 v[20:21], v[18:19], 0, s[44:45]
	v_lshl_add_u64 v[22:23], v[20:21], 0, s[44:45]
	v_lshl_add_u64 v[24:25], v[22:23], 0, s[44:45]
	v_lshl_add_u64 v[26:27], v[24:25], 0, s[44:45]
	v_lshl_add_u64 v[28:29], v[26:27], 0, s[44:45]
	v_lshl_add_u64 v[30:31], v[28:29], 0, s[44:45]
	global_load_dword v32, v[16:17], off nt
	global_load_dword v33, v[18:19], off nt
	global_load_dword v34, v[20:21], off nt
	global_load_dword v35, v[22:23], off nt
	global_load_dword v36, v[24:25], off nt
	global_load_dword v37, v[26:27], off nt
	global_load_dword v38, v[28:29], off nt
	global_load_dword v39, v[30:31], off nt
	v_lshl_add_u64 v[16:17], v[16:17], 0, s[40:41]
	v_lshl_add_u64 v[18:19], v[18:19], 0, s[40:41]
	v_lshl_add_u64 v[20:21], v[20:21], 0, s[40:41]
	v_lshl_add_u64 v[22:23], v[22:23], 0, s[40:41]
	v_lshl_add_u64 v[24:25], v[24:25], 0, s[40:41]
	v_lshl_add_u64 v[26:27], v[26:27], 0, s[40:41]
	v_lshl_add_u64 v[28:29], v[28:29], 0, s[40:41]
	v_lshl_add_u64 v[30:31], v[30:31], 0, s[40:41]
	global_load_dword v40, v[16:17], off nt
	global_load_dword v41, v[18:19], off nt
	global_load_dword v42, v[20:21], off nt
	global_load_dword v43, v[22:23], off nt
	global_load_dword v44, v[24:25], off nt
	global_load_dword v45, v[26:27], off nt
	global_load_dword v46, v[28:29], off nt
	global_load_dword v47, v[30:31], off nt
	v_lshl_add_u64 v[16:17], v[16:17], 0, s[40:41]
	v_lshl_add_u64 v[18:19], v[18:19], 0, s[40:41]
	v_lshl_add_u64 v[20:21], v[20:21], 0, s[40:41]
; #define WAVE_LDS_SYNC() do { int _z = 0; (void)emu::wave_xchg(&_z, 4); } while (0)
; #define LAS __attribute__((address_space(3)))
; #define WAVE_LDS_SYNC() asm volatile("s_waitcnt lgkmcnt(0)" ::: "memory")
; #define NT_LOAD(p) __builtin_nontemporal_load(p)
; #define NT_STORE(v, p) __builtin_nontemporal_store((v), (p))
; DEV unsigned pk2(float lo, float hi) { return f2bf(lo) | (f2bf(hi) << 16); }
; DEV unsigned pk2(float lo, float hi) { const f32x2n_t v = {lo, hi}; return __builtin_bit_cast(unsigned, __builtin_convertvector(v, bf16x2n_t)); }
; DEV void tr_item(const float* W, int ldw, int col0, int k0, bf16_t* WT, int K, int row0, LAS float* scr, int lane) {
;     ...
;     for (int i = 0; i < 32; ++i) { const int kk = 2 * i + (lane >> 5); scr[kk * 33 + (lane & 31)] = NT_LOAD(&W[(size_t)(k0 + kk) * ldw + col0 + (lane & 31)]); }
;     WAVE_LDS_SYNC();
;     const int c = lane & 7;
; #pragma unroll
;     for (int j = 0; j < 4; ++j) { const int n = (lane >> 3) + 8 * j; const LAS float* s = scr + (8 * c) * 33 + n;
;         u32x4 o; o.x = pk2(s[0 * 33], s[1 * 33]); o.y = pk2(s[2 * 33], s[3 * 33]); o.z = pk2(s[4 * 33], s[5 * 33]); o.w = pk2(s[6 * 33], s[7 * 33]);
;         NT_STORE(o, (u32x4*)(WT + (size_t)(row0 + n) * K + k0 + 8 * c)); }
;     WAVE_LDS_SYNC();
; DEV void phase_prologue_a(const Frame& F0) {
;     ...
;         constexpr int GU_NB = 2 * FF / 32, GU_ITEMS = 16 * GU_NB;
;         for (int it = F.gw; it < NE * GU_ITEMS; it += F.NGW) { const int e = it / GU_ITEMS, r = it % GU_ITEMS, kb = r / GU_NB, nb = r % GU_NB; const int d0 = 32 * nb, j = d0 >> 8, w = d0 & 255;
;             const float* src = (w < 128 ? GIN(I_WGATE) : GIN(I_WUP)) + ((size_t)l * NE + e) * 1024 * FF;
;             tr_item(src, FF, 128 * j + (w & 127), 64 * kb, (bf16_t*)(F.ws + WS_WGU) + ((size_t)l * NE + e) * 2 * FF * 1024, 1024, d0, scr, F.lane); }
	v_lshl_add_u64 v[22:23], v[22:23], 0, s[40:41]
	v_lshl_add_u64 v[24:25], v[24:25], 0, s[40:41]
	v_lshl_add_u64 v[26:27], v[26:27], 0, s[40:41]
	v_lshl_add_u64 v[28:29], v[28:29], 0, s[40:41]
	v_lshl_add_u64 v[30:31], v[30:31], 0, s[40:41]
	global_load_dword v48, v[16:17], off nt
	global_load_dword v49, v[18:19], off nt
	global_load_dword v50, v[20:21], off nt
	global_load_dword v51, v[22:23], off nt
	global_load_dword v52, v[24:25], off nt
	global_load_dword v53, v[26:27], off nt
	global_load_dword v54, v[28:29], off nt
	global_load_dword v55, v[30:31], off nt
	v_lshl_add_u64 v[16:17], v[16:17], 0, s[40:41]
	v_lshl_add_u64 v[18:19], v[18:19], 0, s[40:41]
	v_lshl_add_u64 v[20:21], v[20:21], 0, s[40:41]
	v_lshl_add_u64 v[22:23], v[22:23], 0, s[40:41]
	v_lshl_add_u64 v[24:25], v[24:25], 0, s[40:41]
	v_lshl_add_u64 v[26:27], v[26:27], 0, s[40:41]
	v_lshl_add_u64 v[28:29], v[28:29], 0, s[40:41]
	v_lshl_add_u64 v[30:31], v[30:31], 0, s[40:41]
	global_load_dword v56, v[16:17], off nt
	global_load_dword v57, v[18:19], off nt
	global_load_dword v58, v[20:21], off nt
	global_load_dword v59, v[22:23], off nt
	global_load_dword v60, v[24:25], off nt
	global_load_dword v61, v[26:27], off nt
	global_load_dword v62, v[28:29], off nt
	global_load_dword v63, v[30:31], off nt
	v_lshl_add_u64 v[64:65], s[10:11], 0, v[124:125]
	v_lshl_add_u64 v[66:67], v[64:65], 0, s[42:43]
	v_lshl_add_u64 v[68:69], v[66:67], 0, s[42:43]
	v_lshl_add_u64 v[70:71], v[68:69], 0, s[42:43]
	s_add_i32 s31, s2, 0x200
	s_lshr_b32 s8, s31, 11
	s_and_b32 s9, s31, 0x7ff
	s_lshr_b32 s10, s9, 7
	s_and_b32 s9, s9, 0x7f
	s_lshl_b32 s24, s10, 19
	s_lshr_b32 s25, s9, 3
	s_lshl_b32 s25, s25, 9
	s_add_i32 s24, s24, s25
	s_and_b32 s25, s9, 3
	s_lshl_b32 s25, s25, 7
	s_add_i32 s24, s24, s25
	s_lshr_b32 s29, s8, 9
	s_lshl_b32 s28, s8, 23
	s_add_u32 s28, s28, s24
	s_addc_u32 s29, s29, 0
	s_bitcmp0_b32 s9, 2
	s_cselect_b32 s24, s4, s34
	s_cselect_b32 s25, s5, s35
	s_add_u32 s28, s28, s24
	s_addc_u32 s29, s29, s25
	s_lshl_b32 s24, s9, 16
	s_lshl_b32 s25, s10, 7
	s_add_i32 s24, s24, s25
	s_lshr_b32 s11, s8, 9
	s_lshl_b32 s10, s8, 23
	s_add_u32 s10, s10, s24
	s_addc_u32 s11, s11, 0
	s_add_u32 s10, s10, s6
	s_addc_u32 s11, s11, s7
	v_lshl_add_u64 v[16:17], s[28:29], 0, v[122:123]
	v_lshl_add_u64 v[18:19], v[16:17], 0, s[44:45]
	v_lshl_add_u64 v[20:21], v[18:19], 0, s[44:45]
	v_lshl_add_u64 v[22:23], v[20:21], 0, s[44:45]
	v_lshl_add_u64 v[24:25], v[22:23], 0, s[44:45]
	v_lshl_add_u64 v[26:27], v[24:25], 0, s[44:45]
	v_lshl_add_u64 v[28:29], v[26:27], 0, s[44:45]
	v_lshl_add_u64 v[30:31], v[28:29], 0, s[44:45]
	global_load_dword v126, v[16:17], off nt
	global_load_dword v127, v[18:19], off nt
	global_load_dword v128, v[20:21], off nt
	global_load_dword v129, v[22:23], off nt
	global_load_dword v130, v[24:25], off nt
	global_load_dword v131, v[26:27], off nt
	global_load_dword v132, v[28:29], off nt
	global_load_dword v133, v[30:31], off nt
	v_lshl_add_u64 v[16:17], v[16:17], 0, s[40:41]
	v_lshl_add_u64 v[18:19], v[18:19], 0, s[40:41]
	v_lshl_add_u64 v[20:21], v[20:21], 0, s[40:41]
	v_lshl_add_u64 v[22:23], v[22:23], 0, s[40:41]
	v_lshl_add_u64 v[24:25], v[24:25], 0, s[40:41]
	v_lshl_add_u64 v[26:27], v[26:27], 0, s[40:41]
	v_lshl_add_u64 v[28:29], v[28:29], 0, s[40:41]
	v_lshl_add_u64 v[30:31], v[30:31], 0, s[40:41]
	global_load_dword v134, v[16:17], off nt
	global_load_dword v135, v[18:19], off nt
	global_load_dword v136, v[20:21], off nt
	global_load_dword v137, v[22:23], off nt
	global_load_dword v138, v[24:25], off nt
	global_load_dword v139, v[26:27], off nt
	global_load_dword v140, v[28:29], off nt
	global_load_dword v141, v[30:31], off nt
	v_lshl_add_u64 v[16:17], v[16:17], 0, s[40:41]
	v_lshl_add_u64 v[18:19], v[18:19], 0, s[40:41]
	v_lshl_add_u64 v[20:21], v[20:21], 0, s[40:41]
	v_lshl_add_u64 v[22:23], v[22:23], 0, s[40:41]
	v_lshl_add_u64 v[24:25], v[24:25], 0, s[40:41]
	v_lshl_add_u64 v[26:27], v[26:27], 0, s[40:41]
	v_lshl_add_u64 v[28:29], v[28:29], 0, s[40:41]
	v_lshl_add_u64 v[30:31], v[30:31], 0, s[40:41]
	global_load_dword v142, v[16:17], off nt
	global_load_dword v143, v[18:19], off nt
	global_load_dword v144, v[20:21], off nt
	global_load_dword v145, v[22:23], off nt
	global_load_dword v150, v[24:25], off nt
	global_load_dword v151, v[26:27], off nt
	global_load_dword v152, v[28:29], off nt
	global_load_dword v153, v[30:31], off nt
	v_lshl_add_u64 v[16:17], v[16:17], 0, s[40:41]
	v_lshl_add_u64 v[18:19], v[18:19], 0, s[40:41]
	v_lshl_add_u64 v[20:21], v[20:21], 0, s[40:41]
	v_lshl_add_u64 v[22:23], v[22:23], 0, s[40:41]
	v_lshl_add_u64 v[24:25], v[24:25], 0, s[40:41]
	v_lshl_add_u64 v[26:27], v[26:27], 0, s[40:41]
	v_lshl_add_u64 v[28:29], v[28:29], 0, s[40:41]
	v_lshl_add_u64 v[30:31], v[30:31], 0, s[40:41]
	global_load_dword v154, v[16:17], off nt
	global_load_dword v155, v[18:19], off nt
	global_load_dword v156, v[20:21], off nt
	global_load_dword v157, v[22:23], off nt
	global_load_dword v158, v[24:25], off nt
	global_load_dword v159, v[26:27], off nt
	global_load_dword v160, v[28:29], off nt
	global_load_dword v161, v[30:31], off nt
	v_lshl_add_u64 v[162:163], s[10:11], 0, v[124:125]
	v_lshl_add_u64 v[164:165], v[162:163], 0, s[42:43]
	v_lshl_add_u64 v[166:167], v[164:165], 0, s[42:43]
	v_lshl_add_u64 v[168:169], v[166:167], 0, s[42:43]
	s_waitcnt vmcnt(62)
	ds_write2_b32 v7, v32, v33 offset1:66
	s_waitcnt vmcnt(60)
	ds_write2_b32 v7, v34, v35 offset0:132 offset1:198
	s_waitcnt vmcnt(58)
; #define WAVE_LDS_SYNC() do { int _z = 0; (void)emu::wave_xchg(&_z, 4); } while (0)
; #define LAS __attribute__((address_space(3)))
; #define WAVE_LDS_SYNC() asm volatile("s_waitcnt lgkmcnt(0)" ::: "memory")
; #define NT_LOAD(p) __builtin_nontemporal_load(p)
; #define NT_STORE(v, p) __builtin_nontemporal_store((v), (p))
; DEV unsigned pk2(float lo, float hi) { return f2bf(lo) | (f2bf(hi) << 16); }
; DEV unsigned pk2(float lo, float hi) { const f32x2n_t v = {lo, hi}; return __builtin_bit_cast(unsigned, __builtin_convertvector(v, bf16x2n_t)); }
; DEV void tr_item(const float* W, int ldw, int col0, int k0, bf16_t* WT, int K, int row0, LAS float* scr, int lane) {
;     ...
;     for (int i = 0; i < 32; ++i) { const int kk = 2 * i + (lane >> 5); scr[kk * 33 + (lane & 31)] = NT_LOAD(&W[(size_t)(k0 + kk) * ldw + col0 + (lane & 31)]); }
;     WAVE_LDS_SYNC();
;     const int c = lane & 7;
; #pragma unroll
;     for (int j = 0; j < 4; ++j) { const int n = (lane >> 3) + 8 * j; const LAS float* s = scr + (8 * c) * 33 + n;
;         u32x4 o; o.x = pk2(s[0 * 33], s[1 * 33]); o.y = pk2(s[2 * 33], s[3 * 33]); o.z = pk2(s[4 * 33], s[5 * 33]); o.w = pk2(s[6 * 33], s[7 * 33]);
;         NT_STORE(o, (u32x4*)(WT + (size_t)(row0 + n) * K + k0 + 8 * c)); }
;     WAVE_LDS_SYNC();
; DEV void phase_prologue_a(const Frame& F0) {
;     ...
;         constexpr int GU_NB = 2 * FF / 32, GU_ITEMS = 16 * GU_NB;
;         for (int it = F.gw; it < NE * GU_ITEMS; it += F.NGW) { const int e = it / GU_ITEMS, r = it % GU_ITEMS, kb = r / GU_NB, nb = r % GU_NB; const int d0 = 32 * nb, j = d0 >> 8, w = d0 & 255;
;             const float* src = (w < 128 ? GIN(I_WGATE) : GIN(I_WUP)) + ((size_t)l * NE + e) * 1024 * FF;
;             tr_item(src, FF, 128 * j + (w & 127), 64 * kb, (bf16_t*)(F.ws + WS_WGU) + ((size_t)l * NE + e) * 2 * FF * 1024, 1024, d0, scr, F.lane); }
	ds_write2_b32 v8, v36, v37 offset0:8 offset1:74
	s_waitcnt vmcnt(56)
	ds_write2_b32 v8, v38, v39 offset0:140 offset1:206
	s_waitcnt vmcnt(54)
	ds_write2_b32 v9, v40, v41 offset1:66
	s_waitcnt vmcnt(52)
	ds_write2_b32 v9, v42, v43 offset0:132 offset1:198
	s_waitcnt vmcnt(50)
	ds_write2_b32 v10, v44, v45 offset0:8 offset1:74
	s_waitcnt vmcnt(48)
	ds_write2_b32 v10, v46, v47 offset0:140 offset1:206
	s_waitcnt vmcnt(46)
	ds_write2_b32 v11, v48, v49 offset1:66
	s_waitcnt vmcnt(44)
	ds_write2_b32 v11, v50, v51 offset0:132 offset1:198
	s_waitcnt vmcnt(42)
	ds_write2_b32 v12, v52, v53 offset0:8 offset1:74
	s_waitcnt vmcnt(40)
	ds_write2_b32 v12, v54, v55 offset0:140 offset1:206
	s_waitcnt vmcnt(38)
	ds_write2_b32 v13, v56, v57 offset1:66
	s_waitcnt vmcnt(36)
	ds_write2_b32 v13, v58, v59 offset0:132 offset1:198
	s_waitcnt vmcnt(34)
	ds_write2_b32 v14, v60, v61 offset0:8 offset1:74
	s_waitcnt vmcnt(32)
	ds_write2_b32 v14, v62, v63 offset0:140 offset1:206
	ds_read2_b32 v[72:73], v15 offset1:8
	ds_read2_b32 v[74:75], v15 offset0:33 offset1:41
	ds_read2_b32 v[76:77], v15 offset0:66 offset1:74
	ds_read2_b32 v[78:79], v15 offset0:99 offset1:107
	ds_read2_b32 v[80:81], v15 offset0:132 offset1:140
	ds_read2_b32 v[82:83], v15 offset0:165 offset1:173
	ds_read2_b32 v[84:85], v15 offset0:198 offset1:206
	ds_read2_b32 v[86:87], v15 offset0:231 offset1:239
	ds_read2_b32 v[88:89], v15 offset0:16 offset1:24
	ds_read2_b32 v[90:91], v15 offset0:49 offset1:57
	ds_read2_b32 v[92:93], v15 offset0:82 offset1:90
	ds_read2_b32 v[94:95], v15 offset0:115 offset1:123
	s_waitcnt lgkmcnt(4)
	v_cvt_pk_bf16_f32 v104, v72, v74
	v_cvt_pk_bf16_f32 v105, v76, v78
	v_cvt_pk_bf16_f32 v106, v80, v82
	v_cvt_pk_bf16_f32 v107, v84, v86
	v_cvt_pk_bf16_f32 v108, v73, v75
	v_cvt_pk_bf16_f32 v109, v77, v79
	v_cvt_pk_bf16_f32 v110, v81, v83
	v_cvt_pk_bf16_f32 v111, v85, v87
	ds_read2_b32 v[96:97], v15 offset0:148 offset1:156
	ds_read2_b32 v[98:99], v15 offset0:181 offset1:189
	ds_read2_b32 v[100:101], v15 offset0:214 offset1:222
	ds_read2_b32 v[102:103], v15 offset0:247 offset1:255
	global_store_dwordx4 v[64:65], v[104:107], off nt
	global_store_dwordx4 v[66:67], v[108:111], off nt
	s_waitcnt lgkmcnt(0)
	v_cvt_pk_bf16_f32 v112, v88, v90
	v_cvt_pk_bf16_f32 v113, v92, v94
	v_cvt_pk_bf16_f32 v114, v96, v98
	v_cvt_pk_bf16_f32 v115, v100, v102
	v_cvt_pk_bf16_f32 v116, v89, v91
	v_cvt_pk_bf16_f32 v117, v93, v95
	v_cvt_pk_bf16_f32 v118, v97, v99
	v_cvt_pk_bf16_f32 v119, v101, v103
	global_store_dwordx4 v[68:69], v[112:115], off nt
	global_store_dwordx4 v[70:71], v[116:119], off nt
	s_waitcnt vmcnt(34)
	ds_write2_b32 v7, v126, v127 offset1:66
	s_waitcnt vmcnt(32)
	ds_write2_b32 v7, v128, v129 offset0:132 offset1:198
	s_waitcnt vmcnt(30)
	ds_write2_b32 v8, v130, v131 offset0:8 offset1:74
	s_waitcnt vmcnt(28)
	ds_write2_b32 v8, v132, v133 offset0:140 offset1:206
	s_waitcnt vmcnt(26)
	ds_write2_b32 v9, v134, v135 offset1:66
	s_waitcnt vmcnt(24)
	ds_write2_b32 v9, v136, v137 offset0:132 offset1:198
	s_waitcnt vmcnt(22)
	ds_write2_b32 v10, v138, v139 offset0:8 offset1:74
	s_waitcnt vmcnt(20)
	ds_write2_b32 v10, v140, v141 offset0:140 offset1:206
	s_waitcnt vmcnt(18)
	ds_write2_b32 v11, v142, v143 offset1:66
	s_waitcnt vmcnt(16)
	ds_write2_b32 v11, v144, v145 offset0:132 offset1:198
	s_waitcnt vmcnt(14)
	ds_write2_b32 v12, v150, v151 offset0:8 offset1:74
	s_waitcnt vmcnt(12)
	ds_write2_b32 v12, v152, v153 offset0:140 offset1:206
	s_waitcnt vmcnt(10)
	ds_write2_b32 v13, v154, v155 offset1:66
	s_waitcnt vmcnt(8)
	ds_write2_b32 v13, v156, v157 offset0:132 offset1:198
	s_waitcnt vmcnt(6)
	ds_write2_b32 v14, v158, v159 offset0:8 offset1:74
	s_waitcnt vmcnt(4)
	ds_write2_b32 v14, v160, v161 offset0:140 offset1:206
	ds_read2_b32 v[72:73], v15 offset1:8
	ds_read2_b32 v[74:75], v15 offset0:33 offset1:41
	ds_read2_b32 v[76:77], v15 offset0:66 offset1:74
	ds_read2_b32 v[78:79], v15 offset0:99 offset1:107
	ds_read2_b32 v[80:81], v15 offset0:132 offset1:140
	ds_read2_b32 v[82:83], v15 offset0:165 offset1:173
	ds_read2_b32 v[84:85], v15 offset0:198 offset1:206
	ds_read2_b32 v[86:87], v15 offset0:231 offset1:239
	ds_read2_b32 v[88:89], v15 offset0:16 offset1:24
	ds_read2_b32 v[90:91], v15 offset0:49 offset1:57
	ds_read2_b32 v[92:93], v15 offset0:82 offset1:90
	ds_read2_b32 v[94:95], v15 offset0:115 offset1:123
	s_waitcnt lgkmcnt(4)
	v_cvt_pk_bf16_f32 v104, v72, v74
	v_cvt_pk_bf16_f32 v105, v76, v78
	v_cvt_pk_bf16_f32 v106, v80, v82
	v_cvt_pk_bf16_f32 v107, v84, v86
	v_cvt_pk_bf16_f32 v108, v73, v75
	v_cvt_pk_bf16_f32 v109, v77, v79
	v_cvt_pk_bf16_f32 v110, v81, v83
	v_cvt_pk_bf16_f32 v111, v85, v87
	ds_read2_b32 v[96:97], v15 offset0:148 offset1:156
	ds_read2_b32 v[98:99], v15 offset0:181 offset1:189
	ds_read2_b32 v[100:101], v15 offset0:214 offset1:222
	ds_read2_b32 v[102:103], v15 offset0:247 offset1:255
	global_store_dwordx4 v[162:163], v[104:107], off nt
	global_store_dwordx4 v[164:165], v[108:111], off nt
	s_waitcnt lgkmcnt(0)
	v_cvt_pk_bf16_f32 v112, v88, v90
	v_cvt_pk_bf16_f32 v113, v92, v94
	v_cvt_pk_bf16_f32 v114, v96, v98
	v_cvt_pk_bf16_f32 v115, v100, v102
	v_cvt_pk_bf16_f32 v116, v89, v91
	v_cvt_pk_bf16_f32 v117, v93, v95
	v_cvt_pk_bf16_f32 v118, v97, v99
	v_cvt_pk_bf16_f32 v119, v101, v103
	global_store_dwordx4 v[166:167], v[112:115], off nt
	global_store_dwordx4 v[168:169], v[116:119], off nt
	s_add_i32 s2, s2, 0x400
	s_cmp_lt_u32 s2, s101
	s_cbranch_scc1 .Lsx_loop
